# replace the one cooperative-groups grid sync after the prologue by a tag publish from block 0 + one ordinary XCD barrier
# speedup vs baseline: 1.0122x; 1.0122x over previous
; __device__ __forceinline__ unsigned xb_ld(unsigned* p)              { return __hip_atomic_load(p, __ATOMIC_RELAXED, __HIP_MEMORY_SCOPE_AGENT); }
; __device__ __forceinline__ unsigned xb_add(unsigned* p, unsigned v) { return __hip_atomic_fetch_add(p, v, __ATOMIC_RELAXED, __HIP_MEMORY_SCOPE_AGENT); }
; __device__ __forceinline__ void xcd_barrier_complete(unsigned* bar, unsigned x, unsigned& nloc, unsigned& nx) {
;     const unsigned G = gridDim.x * gridDim.y * gridDim.z;
;     unsigned sum, cnt, mine, sp = 0u;
;     for (;;) {
;         sum = 0u; cnt = 0u; mine = 0u;
; #pragma unroll
;         for (unsigned j = 0; j < 16; ++j) { const unsigned c = xb_ld(&bar[XB_XCNT(j)]); sum += c; cnt += (c > 0u) ? 1u : 0u; mine = (j == x) ? c : mine; }
; __device__ __forceinline__ void xcd_barrier(const XcdBarrier& b) {
;     asm volatile("s_waitcnt vmcnt(0)" ::: "memory");
;     __syncthreads();
;     if (threadIdx.x == 0) {
;         unsigned* bar = b.bar;
;         __builtin_amdgcn_s_waitcnt(0);
;         unsigned nloc = b.st[0], nx = b.st[1];
;         if (nloc == 0u) { xcd_barrier_complete(bar, b.x, nloc, nx); b.st[0] = nloc; b.st[1] = nx; }
;         const unsigned old = xb_add(&bar[XB_XSUB(b.x)], 1u);
.Lxb796:
	s_waitcnt vmcnt(0)
	s_waitcnt vmcnt(0)
	s_barrier
	s_mov_b64 s[6:7], exec
	v_readlane_b32 s2, v254, 7
	v_readlane_b32 s3, v254, 8
	s_and_b64 s[2:3], s[6:7], s[2:3]
	s_mov_b64 exec, s[2:3]
	s_cbranch_execz .LBB0_840
	v_readlane_b32 s0, v254, 5
	s_waitcnt vmcnt(0) expcnt(0) lgkmcnt(0)
	s_nop 0
	v_mov_b32_e32 v0, s0
	ds_read_b32 v2, v0
	ds_read_b32 v0, v0 offset:4
	s_waitcnt lgkmcnt(1)
	v_cmp_ne_u32_e32 vcc, 0, v2
	s_cbranch_vccnz .LBB0_811
	v_readlane_b32 s14, v254, 11
	v_readlane_b32 s15, v254, 12
	s_add_u32 s8, s14, 0x1000
	s_addc_u32 s9, s15, 0
	s_load_dwordx2 s[2:3], s[72:73], 0x0
	s_load_dword s0, s[72:73], 0x8
	s_add_u32 s10, s14, 0x1100
	s_addc_u32 s11, s15, 0
	s_add_u32 s12, s14, 0x1200
	s_addc_u32 s13, s15, 0
	s_waitcnt lgkmcnt(0)
	s_mul_i32 s2, s3, s2
	s_add_u32 s14, s14, 0x1300
	s_mul_i32 s0, s2, s0
	s_addc_u32 s15, s15, 0
	s_mov_b32 s2, 1
	s_branch .LBB0_800

; __global__ void __launch_bounds__(512, 2) mega(Params Pk, int ph_lo, int ph_hi) {
;     ...
;         if (ph + 1 < ph_hi) {
;             if (ph == 0) { cg::this_grid().sync(); bar = xcd_barrier_post((unsigned*)(P->ws + WS_BAR), MISC + 8); }
.LBB0_841:
	s_waitcnt vmcnt(0)
	s_barrier
	s_mov_b64 s[6:7], exec
	v_readlane_b32 s2, v254, 7
	v_readlane_b32 s3, v254, 8
	s_and_b64 s[2:3], s[6:7], s[2:3]
	s_mov_b64 exec, s[2:3]
	s_cbranch_execz .LBB0_851
	v_readlane_b32 s8, v254, 20
	v_readlane_b32 s9, v254, 21
	s_nop 1
	s_add_u32 s8, s8, 0xc010000
	s_addc_u32 s9, s9, 0
	v_mov_b32_e32 v0, 0x5ac3e197
	s_mov_b32 s0, 0
	s_cmp_lg_u32 s98, 0
	s_cbranch_scc1 .Lcg_wait
	buffer_wbl2 sc1
	s_waitcnt vmcnt(0)
	global_atomic_add v169, v0, s[8:9] offset:256
	s_waitcnt vmcnt(0)
.Lcg_wait:
	global_load_dword v1, v169, s[8:9] offset:256 sc1
	s_add_i32 s0, s0, 1
	s_waitcnt vmcnt(0)
	v_cmp_eq_u32_e32 vcc, v1, v0
	s_cbranch_vccnz .LBB0_850
	s_cmp_gt_u32 s0, 0x20000
	s_cbranch_scc1 .LBB0_850
	s_sleep 1
	s_branch .Lcg_wait

; #define LAS __attribute__((address_space(3)))
; __device__ __forceinline__ unsigned xb_add(unsigned* p, unsigned v) { return __hip_atomic_fetch_add(p, v, __ATOMIC_RELAXED, __HIP_MEMORY_SCOPE_AGENT); }
; __device__ __forceinline__ unsigned xb_xcc_id() { return (unsigned)__builtin_amdgcn_s_getreg((3 << 11) | 20) & 0xFu; }
; __device__ __forceinline__ XcdBarrier xcd_barrier_post(unsigned* bar, volatile LAS unsigned* st) {
;     XcdBarrier b; b.bar = bar; b.x = xb_xcc_id(); b.st = st;
;     if (threadIdx.x == 0) (void)xb_add(&bar[XB_XCNT(b.x)], 1u);
;     return b;
; __global__ void __launch_bounds__(512, 2) mega(Params Pk, int ph_lo, int ph_hi) {
;     ...
;         if (ph + 1 < ph_hi) {
;             if (ph == 0) { cg::this_grid().sync(); bar = xcd_barrier_post((unsigned*)(P->ws + WS_BAR), MISC + 8); }
;             else xcd_barrier(bar);
;         }
.Lpost4:
	s_or_b64 exec, exec, s[6:7]
	v_readlane_b32 s0, v254, 4
	s_nop 1
	v_writelane_b32 v254, s0, 5
	s_branch .Lxb796
.Lexit_clear:
	s_cmp_lg_u32 s98, 0
	s_cbranch_scc1 .LBB0_854
	v_readlane_b32 s8, v254, 11
	v_readlane_b32 s9, v254, 12
	s_nop 4
	global_store_dword v169, v169, s[8:9] offset:256
